# attnA block shifted by 4 bytes (alignment phase test), otherwise v7
# baseline (speedup 1.0000x reference)
; #define LAS __attribute__((address_space(3)))
; __device__ __forceinline__ void attnA_unit(const P2Ctx& C, int b, int h, int qb) {
;     LAS unsigned char* lds = C.lds; const int lane = C.lane, wid = C.wid, pf = C.pf;
;     const int comp = wid >> 2, qs = wid & 3, r32 = lane & 31, hi = lane >> 5;
;     const int q0 = qb * 128, trow0 = b * SEQ;
;     const int qpos = q0 + qs * 32 + r32; const size_t qrow = (size_t)(trow0 + qpos);
;     const int qcw = (q0 + qs * 32) >> 6, ntw = qcw + 1, NT = 2 * qb + 2;
;     const LAS float* lut = (const LAS float*)(lds + LUT_OFF) + h * 256;
;     const float lam = *(const LAS float*)(lds + LAM_OFF);
;     bf16x8 qf[4];
; #pragma unroll
;     for (int ds = 0; ds < 4; ++ds) qf[ds] = *(const bf16x8*)(C.Q + qrow * DM + h * 128 + comp * 64 + ds * 16 + hi * 8);
;     const int kkey = 8 * wid + (lane >> 3), kchs = (lane & 7) ^ ((kkey >> 1) & 7);
;     const bf16_t* ksrc = C.Kb + ((size_t)trow0 + kkey) * DM + h * 128 + kchs * 8;
;     const bf16_t* vsrc[2];
; #pragma unroll
;     for (int i = 0; i < 2; ++i) { const int p = 2 * wid + i, kg = p >> 1, cbv = 2 * (p & 1) + (lane >> 5), vkey = kg * 8 + ((lane >> 2) & 7), vch = cbv * 4 + (lane & 3);
;         vsrc[i] = C.Vb + ((size_t)trow0 + vkey) * DM + h * 128 + vch * 8; }
;     ...
;     A_DMA(0); A_DMA(1);
.LBB0_572:
	s_andn2_b64 vcc, exec, s[6:7]
	s_cbranch_vccnz .LBB0_614
	s_nop 0
	s_sub_i32 s6, s37, 32
	s_and_b32 s11, s6, 7
	s_lshr_b32 s6, s6, 3
	s_sub_i32 s10, 15, s6
	s_lshr_b32 s8, s83, 2
	s_and_b32 s9, s83, 3
	s_lshl_b32 s12, s10, 1
	s_add_i32 s12, s12, 2
	s_lshr_b32 s6, s9, 1
	s_lshl_b32 s13, s10, 1
	s_add_i32 s13, s13, s6
	s_add_i32 s13, s13, 1
	s_lshl_b32 s22, s83, 10
	s_lshl_b32 s23, s83, 11
	s_add_i32 s23, s23, 0x4000
	s_lshl_b32 s6, s10, 7
	s_lshl_b32 s7, s9, 5
	s_add_i32 s15, s6, s7
	s_add_i32 s26, s15, 0xffffff01
	s_mov_b32 s25, 0
	v_and_b32_e32 v100, 31, v219
	v_lshrrev_b32_e32 v101, 5, v219
	s_load_dwordx2 s[20:21], s[62:63], 0x80
	v_lshlrev_b32_e32 v107, 4, v196
	s_waitcnt lgkmcnt(0)
	v_cmp_gt_u32_e32 vcc, 32, v196
	s_and_saveexec_b64 s[6:7], vcc
	global_load_dwordx4 v[108:111], v107, s[20:21]
	s_or_b64 exec, exec, s[6:7]
	s_lshl_b32 s6, s11, 11
	s_add_i32 s6, s6, s15
	s_lshl_b32 s6, s6, 11
	s_lshl_b32 s7, s81, 1
	s_add_i32 s6, s6, s7
	s_lshl_b32 s7, s8, 7
	s_add_i32 s6, s6, s7
	s_add_u32 s20, s76, s6
	s_addc_u32 s21, s77, 0
	v_lshlrev_b32_e32 v102, 11, v100
	v_lshl_add_u32 v102, v101, 4, v102
	global_load_dwordx4 v[164:167], v102, s[20:21]
	global_load_dwordx4 v[168:171], v102, s[20:21] offset:32
	global_load_dwordx4 v[172:175], v102, s[20:21] offset:64
	global_load_dwordx4 v[176:179], v102, s[20:21] offset:96
	s_lshl_b32 s6, s11, 22
	s_lshl_b32 s7, s81, 1
	s_add_i32 s6, s6, s7
	s_add_u32 s16, s72, s6
	s_addc_u32 s17, s73, 0
	s_add_u32 s18, s74, s6
	s_addc_u32 s19, s75, 0
	s_mov_b32 s24, 0
	v_lshrrev_b32_e32 v103, 3, v219
	s_lshl_b32 s6, s83, 3
	v_add_u32_e32 v103, s6, v103
	v_bfe_u32 v104, v103, 1, 3
	v_and_b32_e32 v105, 7, v219
	v_xor_b32_e32 v104, v104, v105
	v_lshlrev_b32_e32 v104, 4, v104
	v_lshl_add_u32 v197, v103, 11, v104
	v_bfe_u32 v103, v219, 2, 3
	v_add_u32_e32 v103, s6, v103
	v_and_b32_e32 v104, 3, v219
	v_lshlrev_b32_e32 v104, 4, v104
	v_lshl_add_u32 v104, v101, 6, v104
	v_lshl_add_u32 v198, v103, 11, v104
	s_and_b32 s6, s24, 3
	s_lshl_b32 s6, s6, 15
	s_add_i32 s7, s6, s22
	s_mov_b32 m0, s7
	s_add_u32 s20, s16, 0x80
	s_addc_u32 s21, s17, 0
	s_add_i32 s29, s6, s23
	global_load_lds_dwordx4 v197, s[16:17]
	s_add_i32 m0, s7, 0x2000
	s_add_u32 s16, s16, 0x20000
	s_addc_u32 s17, s17, 0
	s_nop 0
	global_load_lds_dwordx4 v197, s[20:21]
	s_mov_b32 m0, s29
	s_add_u32 s20, s18, 0x80
	s_addc_u32 s21, s19, 0
	s_nop 0
	global_load_lds_dwordx4 v198, s[18:19]
	s_add_i32 m0, s29, 0x400
	s_add_u32 s18, s18, 0x20000
	s_addc_u32 s19, s19, 0
	s_add_i32 s24, s24, 1
	global_load_lds_dwordx4 v198, s[20:21]
	s_and_b32 s6, s24, 3
	s_lshl_b32 s6, s6, 15
	s_add_i32 s7, s6, s22
	s_mov_b32 m0, s7
	s_add_u32 s20, s16, 0x80
	s_addc_u32 s21, s17, 0
	s_add_i32 s29, s6, s23
	global_load_lds_dwordx4 v197, s[16:17]
	s_add_i32 m0, s7, 0x2000
	s_add_u32 s16, s16, 0x20000
	s_addc_u32 s17, s17, 0
	s_nop 0
	global_load_lds_dwordx4 v197, s[20:21]
	s_mov_b32 m0, s29
	s_add_u32 s20, s18, 0x80
	s_addc_u32 s21, s19, 0
	s_nop 0
	global_load_lds_dwordx4 v198, s[18:19]
	s_add_i32 m0, s29, 0x400
	s_add_u32 s18, s18, 0x20000
	s_addc_u32 s19, s19, 0
	s_add_i32 s24, s24, 1
	global_load_lds_dwordx4 v198, s[20:21]
	v_bfe_u32 v103, v100, 1, 3
	v_lshlrev_b32_e32 v104, 7, v100
	s_lshl_b32 s6, s8, 13
	v_add_u32_e32 v104, s6, v104
	v_or_b32_e32 v105, 0, v101
	v_xor_b32_e32 v105, v105, v103
	v_lshl_add_u32 v200, v105, 4, v104
	v_or_b32_e32 v105, 2, v101
	v_xor_b32_e32 v105, v105, v103
	v_lshl_add_u32 v201, v105, 4, v104
	v_or_b32_e32 v105, 4, v101
	v_xor_b32_e32 v105, v105, v103
	v_lshl_add_u32 v202, v105, 4, v104
	v_or_b32_e32 v105, 6, v101
	v_xor_b32_e32 v105, v105, v103
	v_lshl_add_u32 v203, v105, 4, v104
	v_bfe_u32 v103, v219, 2, 2
	v_lshl_add_u32 v103, v101, 2, v103
	v_lshlrev_b32_e32 v103, 6, v103
	v_bfe_u32 v104, v219, 4, 1
	v_lshl_add_u32 v103, v104, 5, v103
	v_and_b32_e32 v104, 3, v219
	v_lshl_add_u32 v103, v104, 3, v103
	v_add_u32_e32 v204, 0x4000, v103
	s_sub_i32 s6, 0x120, s15
	s_lshl_b32 s6, s6, 2
	s_add_i32 s6, s6, 0x22400
	v_lshlrev_b32_e32 v103, 4, v101
	v_lshlrev_b32_e32 v104, 2, v100
	v_sub_u32_e32 v103, v103, v104
	v_add_u32_e32 v236, s6, v103
	v_cmp_gt_u32_e32 vcc, 0x160, v196
	s_and_saveexec_b64 s[6:7], vcc
	s_cbranch_execz .LaA_padskip_1
	v_subrev_u32_e32 v103, 0x60, v196
	v_max_i32_e32 v104, 0, v103
	v_lshl_add_u32 v104, v104, 2, s42
	ds_read_b32 v105, v104
	v_cmp_gt_i32_e32 vcc, 0, v103
	v_mov_b32_e32 v106, 0x22400
	v_lshl_add_u32 v104, v196, 2, v106
	s_waitcnt lgkmcnt(0)
	v_cndmask_b32_e64 v105, v105, 0, vcc
	ds_write_b32 v104, v105

; #define LAS __attribute__((address_space(3)))
; __device__ __forceinline__ void attnA_unit(const P2Ctx& C, int b, int h, int qb) {
;     ...
;     __syncthreads();
;     ...
;     l += __shfl_xor(l, 32);
;     const float inv = 1.0f / l;
;     LAS float* X2 = (LAS float*)(lds + 65536);
;     if (comp == 1) {
; #pragma unroll
;         for (int cb = 0; cb < 4; ++cb)
; #pragma unroll
;             for (int r = 0; r < 16; ++r) X2[((qs * 4 + cb) * 16 + r) * 64 + lane] = o[cb][r] * inv;
;     }
.LaA_nofinalpv_13:
	s_waitcnt lgkmcnt(0)
	s_barrier
	v_mov_b32_e32 v243, v241
	s_nop 1
	v_permlane32_swap_b32 v243, v241
	v_add_f32_e32 v241, v243, v241
	v_rcp_f32_e32 v241, v241
	s_lshl_b32 s6, s9, 14
	s_add_i32 s6, s6, 0x10000
	v_lshlrev_b32_e32 v2, 2, v219
	v_add_u32_e32 v2, s6, v2
	s_cmp_eq_u32 s8, 0
	s_cbranch_scc1 .LaA_comp0_14
	s_nop 7
	s_nop 3
	v_mul_f32_e32 v68, v4, v241
	ds_write_b32 v2, v68 offset:0
	v_mul_f32_e32 v69, v5, v241
	ds_write_b32 v2, v69 offset:256
	v_mul_f32_e32 v68, v6, v241
	ds_write_b32 v2, v68 offset:512
	v_mul_f32_e32 v69, v7, v241
	ds_write_b32 v2, v69 offset:768
	v_mul_f32_e32 v68, v8, v241
	ds_write_b32 v2, v68 offset:1024
	v_mul_f32_e32 v69, v9, v241
	ds_write_b32 v2, v69 offset:1280
	v_mul_f32_e32 v68, v10, v241
	ds_write_b32 v2, v68 offset:1536
	v_mul_f32_e32 v69, v11, v241
	ds_write_b32 v2, v69 offset:1792
	v_mul_f32_e32 v68, v12, v241
	ds_write_b32 v2, v68 offset:2048
	v_mul_f32_e32 v69, v13, v241
	ds_write_b32 v2, v69 offset:2304
	v_mul_f32_e32 v68, v14, v241
	ds_write_b32 v2, v68 offset:2560
	v_mul_f32_e32 v69, v15, v241
	ds_write_b32 v2, v69 offset:2816
	v_mul_f32_e32 v68, v16, v241
	ds_write_b32 v2, v68 offset:3072
	v_mul_f32_e32 v69, v17, v241
	ds_write_b32 v2, v69 offset:3328
	v_mul_f32_e32 v68, v18, v241
	ds_write_b32 v2, v68 offset:3584
	v_mul_f32_e32 v69, v19, v241
	ds_write_b32 v2, v69 offset:3840
	v_mul_f32_e32 v68, v20, v241
	ds_write_b32 v2, v68 offset:4096
	v_mul_f32_e32 v69, v21, v241
	ds_write_b32 v2, v69 offset:4352
	v_mul_f32_e32 v68, v22, v241
	ds_write_b32 v2, v68 offset:4608
	v_mul_f32_e32 v69, v23, v241
	ds_write_b32 v2, v69 offset:4864
	v_mul_f32_e32 v68, v24, v241
	ds_write_b32 v2, v68 offset:5120
	v_mul_f32_e32 v69, v25, v241
	ds_write_b32 v2, v69 offset:5376
	v_mul_f32_e32 v68, v26, v241
	ds_write_b32 v2, v68 offset:5632
	v_mul_f32_e32 v69, v27, v241
	ds_write_b32 v2, v69 offset:5888
	v_mul_f32_e32 v68, v28, v241
	ds_write_b32 v2, v68 offset:6144
	v_mul_f32_e32 v69, v29, v241
	ds_write_b32 v2, v69 offset:6400
	v_mul_f32_e32 v68, v30, v241
	ds_write_b32 v2, v68 offset:6656
	v_mul_f32_e32 v69, v31, v241
	ds_write_b32 v2, v69 offset:6912
	v_mul_f32_e32 v68, v32, v241
	ds_write_b32 v2, v68 offset:7168
	v_mul_f32_e32 v69, v33, v241
	ds_write_b32 v2, v69 offset:7424
	v_mul_f32_e32 v68, v34, v241
	ds_write_b32 v2, v68 offset:7680
	v_mul_f32_e32 v69, v35, v241
	ds_write_b32 v2, v69 offset:7936
	v_mul_f32_e32 v68, v36, v241
	ds_write_b32 v2, v68 offset:8192
	v_mul_f32_e32 v69, v37, v241
	ds_write_b32 v2, v69 offset:8448
	v_mul_f32_e32 v68, v38, v241
	ds_write_b32 v2, v68 offset:8704
	v_mul_f32_e32 v69, v39, v241
	ds_write_b32 v2, v69 offset:8960
	v_mul_f32_e32 v68, v40, v241
	ds_write_b32 v2, v68 offset:9216
	v_mul_f32_e32 v69, v41, v241
	ds_write_b32 v2, v69 offset:9472
	v_mul_f32_e32 v68, v42, v241
	ds_write_b32 v2, v68 offset:9728
	v_mul_f32_e32 v69, v43, v241
	ds_write_b32 v2, v69 offset:9984
	v_mul_f32_e32 v68, v44, v241
	ds_write_b32 v2, v68 offset:10240
	v_mul_f32_e32 v69, v45, v241
	ds_write_b32 v2, v69 offset:10496
	v_mul_f32_e32 v68, v46, v241
	ds_write_b32 v2, v68 offset:10752
	v_mul_f32_e32 v69, v47, v241
	ds_write_b32 v2, v69 offset:11008
	v_mul_f32_e32 v68, v48, v241
	ds_write_b32 v2, v68 offset:11264
	v_mul_f32_e32 v69, v49, v241
	ds_write_b32 v2, v69 offset:11520
	v_mul_f32_e32 v68, v50, v241
	ds_write_b32 v2, v68 offset:11776
	v_mul_f32_e32 v69, v51, v241
	ds_write_b32 v2, v69 offset:12032
	v_mul_f32_e32 v68, v52, v241
	ds_write_b32 v2, v68 offset:12288
	v_mul_f32_e32 v69, v53, v241
	ds_write_b32 v2, v69 offset:12544
	v_mul_f32_e32 v68, v54, v241
	ds_write_b32 v2, v68 offset:12800
	v_mul_f32_e32 v69, v55, v241
	ds_write_b32 v2, v69 offset:13056
	v_mul_f32_e32 v68, v56, v241
	ds_write_b32 v2, v68 offset:13312
	v_mul_f32_e32 v69, v57, v241
	ds_write_b32 v2, v69 offset:13568
	v_mul_f32_e32 v68, v58, v241
	ds_write_b32 v2, v68 offset:13824
	v_mul_f32_e32 v69, v59, v241
	ds_write_b32 v2, v69 offset:14080
	v_mul_f32_e32 v68, v60, v241
	ds_write_b32 v2, v68 offset:14336
	v_mul_f32_e32 v69, v61, v241
	ds_write_b32 v2, v69 offset:14592
	v_mul_f32_e32 v68, v62, v241
	ds_write_b32 v2, v68 offset:14848
	v_mul_f32_e32 v69, v63, v241
	ds_write_b32 v2, v69 offset:15104
	v_mul_f32_e32 v68, v64, v241
	ds_write_b32 v2, v68 offset:15360
	v_mul_f32_e32 v69, v65, v241
	ds_write_b32 v2, v69 offset:15616
	v_mul_f32_e32 v68, v66, v241
	ds_write_b32 v2, v68 offset:15872
	v_mul_f32_e32 v69, v67, v241
	ds_write_b32 v2, v69 offset:16128
	s_waitcnt lgkmcnt(0)
	s_barrier
	s_branch .LaA_epiend_15
; __device__ __forceinline__ void attnA_unit(const P2Ctx& C, int b, int h, int qb) {
;     ...
;     if (comp == 1) {
; #pragma unroll
;         for (int cb = 0; cb < 4; ++cb)
; #pragma unroll
;             for (int r = 0; r < 16; ++r) X2[((qs * 4 + cb) * 16 + r) * 64 + lane] = o[cb][r] * inv;
;     }
	s_nop 0
	s_nop 0
	s_nop 0
	s_nop 0
	s_nop 0
	s_nop 0
	s_nop 0
	s_nop 0
	s_nop 0
	s_nop 0
	s_nop 0
	s_nop 0
	s_nop 0
	s_nop 0
	s_nop 0
	s_nop 0
	s_nop 0
	s_nop 0
	s_nop 0
	s_nop 0
	s_nop 0
	s_nop 0
	s_nop 0
	s_nop 0
	s_nop 0
	s_nop 0
	s_nop 0
	s_nop 0
	s_nop 0
	s_nop 0
	s_nop 0
	s_nop 0
	s_nop 0
	s_nop 0
	s_nop 0
	s_nop 0
	s_nop 0
	s_nop 0
	s_nop 0
	s_nop 0
	s_nop 0
	s_nop 0
	s_nop 0
	s_nop 0
	s_nop 0
	s_nop 0
	s_nop 0
	s_nop 0
	s_nop 0
	s_nop 0
	s_nop 0
	s_nop 0
	s_nop 0
	s_nop 0
	s_nop 0
	s_nop 0
	s_nop 0
	s_nop 0
	s_nop 0
	s_nop 0
	s_nop 0
	s_nop 0
	s_nop 0
	s_nop 0
	s_nop 0
	s_nop 0
	s_nop 0
	s_nop 0
	s_nop 0
	s_nop 0
	s_nop 0
	s_nop 0
	s_nop 0
	s_nop 0
	s_nop 0
	s_nop 0
	s_nop 0
	s_nop 0
	s_nop 0
	s_nop 0
	s_nop 0
	s_nop 0
	s_nop 0
	s_nop 0
	s_nop 0
	s_nop 0
	s_nop 0
	s_nop 0
	s_nop 0
	s_nop 0
	s_nop 0
	s_nop 0
	s_nop 0
	s_nop 0
	s_nop 0
	s_nop 0
	s_nop 0
	s_nop 0
	s_nop 0
	s_nop 0
	s_nop 0
	s_nop 0
	s_nop 0
	s_nop 0
	s_nop 0
	s_nop 0
	s_nop 0
	s_nop 0
	s_nop 0
	s_nop 0
	s_nop 0
	s_nop 0
	s_nop 0
	s_nop 0
	s_nop 0
	s_nop 0
	s_nop 0
	s_nop 0
	s_nop 0
	s_nop 0
	s_nop 0
	s_nop 0
	s_nop 0
	s_nop 0
	s_nop 0
	s_nop 0
	s_nop 0
	s_nop 0
	s_nop 0
	s_nop 0
	s_nop 0
	s_nop 0
	s_nop 0
	s_nop 0
	s_nop 0
	s_nop 0
	s_nop 0
	s_nop 0
	s_nop 0
	s_nop 0
	s_nop 0
	s_nop 0
	s_nop 0
	s_nop 0
	s_nop 0
	s_nop 0
	s_nop 0
	s_nop 0
	s_nop 0
	s_nop 0
	s_nop 0
	s_nop 0
	s_nop 0
	s_nop 0
	s_nop 0
	s_nop 0
	s_nop 0
	s_nop 0
	s_nop 0
	s_nop 0
	s_nop 0
	s_nop 0
	s_nop 0
	s_nop 0
	s_nop 0
	s_nop 0
	s_nop 0
	s_nop 0
	s_nop 0
	s_nop 0
	s_nop 0
	s_nop 0
	s_nop 0
	s_nop 0
	s_nop 0
	s_nop 0
	s_nop 0
	s_nop 0
	s_nop 0
	s_nop 0
	s_nop 0
	s_nop 0
	s_nop 0
	s_nop 0
	s_nop 0
	s_nop 0
	s_nop 0
	s_nop 0
	s_nop 0
	s_nop 0
	s_nop 0
	s_nop 0
	s_nop 0
	s_nop 0
	s_nop 0
	s_nop 0
	s_nop 0
	s_nop 0
	s_nop 0
	s_nop 0
	s_nop 0
	s_nop 0
	s_nop 0
	s_nop 0
	s_nop 0
	s_nop 0
	s_nop 0
	s_nop 0
	s_nop 0
	s_nop 0
	s_nop 0
	s_nop 0
	s_nop 0
	s_nop 0
	s_nop 0
	s_nop 0
	s_nop 0
	s_nop 0
	s_nop 0
	s_nop 0
	s_nop 0
	s_nop 0
	s_nop 0
	s_nop 0
	s_nop 0
	s_nop 0
	s_nop 0
	s_nop 0
	s_nop 0
	s_nop 0
	s_nop 0
	s_nop 0
	s_nop 0
	s_nop 0
	s_nop 0
	s_nop 0
	s_nop 0
	s_nop 0
	s_nop 0
	s_nop 0
	s_nop 0
	s_nop 0
	s_nop 0
	s_nop 0
	s_nop 0
	s_nop 0
	s_nop 0
	s_nop 0
	s_nop 0
	s_nop 0
	s_nop 0
	s_nop 0
	s_nop 0
	s_nop 0
	s_nop 0
	s_nop 0
	s_nop 0
	s_nop 0
	s_nop 0
	s_nop 0
	s_nop 0
	s_nop 0
	s_nop 0
	s_nop 0
	s_nop 0
	s_nop 0
	s_nop 0
	s_nop 0
	s_nop 0
	s_nop 0
	s_nop 0
	s_nop 0
	s_nop 0
	s_nop 0
	s_nop 0
	s_nop 0
	s_nop 0
	s_nop 0
	s_nop 0
	s_nop 0
	s_nop 0
	s_nop 0
	s_nop 0
	s_nop 0
	s_nop 0
	s_nop 0
	s_nop 0
	s_nop 0
	s_nop 0
	s_nop 0
	s_nop 0
	s_nop 0
	s_nop 0
	s_nop 0
	s_nop 0
	s_nop 0
	s_nop 0
	s_nop 0
	s_nop 0
	s_nop 0
	s_nop 0
	s_nop 0
	s_nop 0
	s_nop 0
	s_nop 0
	s_nop 0
	s_nop 0
	s_nop 0
	s_nop 0
	s_nop 0
	s_nop 0
	s_nop 0
	s_nop 0
	s_nop 0
	s_nop 0
	s_nop 0
	s_nop 0
	s_nop 0
	s_nop 0
	s_nop 0
	s_nop 0
	s_nop 0
	s_nop 0
	s_nop 0
	s_nop 0
	s_nop 0
	s_nop 0
	s_nop 0
	s_nop 0
	s_nop 0
	s_nop 0
	s_nop 0
	s_nop 0
	s_nop 0
	s_nop 0
	s_nop 0
	s_nop 0
	s_nop 0
	s_nop 0
	s_nop 0
	s_nop 0
	s_nop 0
	s_nop 0
	s_nop 0
	s_nop 0
	s_nop 0
	s_nop 0
	s_nop 0
	s_nop 0
	s_nop 0
	s_nop 0
	s_nop 0
	s_nop 0
	s_nop 0
	s_nop 0
	s_nop 0
	s_nop 0
	s_nop 0
	s_nop 0
	s_nop 0
	s_nop 0
	s_nop 0
	s_nop 0
	s_nop 0
	s_nop 0
	s_nop 0
	s_nop 0
	s_nop 0
	s_nop 0
	s_nop 0
	s_nop 0
	s_nop 0
	s_nop 0
	s_nop 0
	s_nop 0
	s_nop 0
	s_nop 0
	s_nop 0
	s_nop 0
	s_nop 0
	s_nop 0
	s_nop 0
	s_nop 0
	s_nop 0
	s_nop 0
	s_nop 0
	s_nop 0
	s_nop 0
	s_nop 0
	s_nop 0
	s_nop 0
	s_nop 0
	s_nop 0
	s_nop 0
	s_nop 0
	s_nop 0
	s_nop 0
	s_nop 0
	s_nop 0
	s_nop 0
	s_nop 0
	s_nop 0
	s_nop 0
	s_nop 0
	s_nop 0
	s_nop 0
	s_nop 0
	s_nop 0
	s_nop 0
	s_nop 0
	s_nop 0
	s_nop 0
	s_nop 0
	s_nop 0
	s_nop 0
	s_nop 0
	s_nop 0
	s_nop 0
	s_nop 0
	s_nop 0
	s_nop 0
	s_nop 0
	s_nop 0
	s_nop 0
	s_nop 0
	s_nop 0
	s_nop 0
	s_nop 0
	s_nop 0
	s_nop 0
	s_nop 0
	s_nop 0
	s_nop 0
	s_nop 0
	s_nop 0
	s_nop 0
	s_nop 0
	s_nop 0
	s_nop 0
	s_nop 0
	s_nop 0
	s_nop 0
	s_nop 0
	s_nop 0
	s_nop 0
	s_nop 0
	s_nop 0
	s_nop 0
	s_nop 0
	s_nop 0
	s_nop 0
	s_nop 0
	s_nop 0
	s_nop 0
	s_nop 0
	s_nop 0
	s_nop 0
	s_nop 0
	s_nop 0
	s_nop 0
	s_nop 0
	s_nop 0
	s_nop 0
	s_nop 0
	s_nop 0
	s_nop 0
	s_nop 0
	s_nop 0
	s_nop 0
	s_nop 0
	s_nop 0
	s_nop 0
	s_nop 0
	s_nop 0
	s_nop 0
	s_nop 0
	s_nop 0
	s_nop 0
	s_nop 0
	s_nop 0
	s_nop 0
	s_nop 0
	s_nop 0
	s_nop 0
	s_nop 0
	s_nop 0
	s_nop 0
	s_nop 0
	s_nop 0
	s_nop 0
	s_nop 0
	s_nop 0
	s_nop 0
	s_nop 0
	s_nop 0
	s_nop 0
	s_nop 0
	s_nop 0
	s_nop 0
	s_nop 0
	s_nop 0
	s_nop 0
	s_nop 0
	s_nop 0
	s_nop 0
	s_nop 0
	s_nop 0
	s_nop 0
	s_nop 0
	s_nop 0
	s_nop 0
	s_nop 0
	s_nop 0
	s_nop 0
	s_nop 0
	s_nop 0
	s_nop 0
	s_nop 0
	s_nop 0
	s_nop 0
	s_nop 0
	s_nop 0
	s_nop 0
	s_nop 0
	s_nop 0
	s_nop 0
	s_nop 0
	s_nop 0
	s_nop 0
	s_nop 0
	s_nop 0
	s_nop 0
	s_nop 0
	s_nop 0
	s_nop 0
	s_nop 0
	s_nop 0
	s_nop 0
	s_nop 0
	s_nop 0
	s_nop 0
	s_nop 0
	s_nop 0
	s_nop 0
	s_nop 0
	s_nop 0
	s_nop 0
	s_nop 0
	s_nop 0
	s_nop 0
	s_nop 0
	s_nop 0
	s_nop 0
	s_nop 0
	s_nop 0
	s_nop 0
	s_nop 0
	s_nop 0
	s_nop 0
	s_nop 0
	s_nop 0
	s_nop 0
	s_nop 0
	s_nop 0
	s_nop 0
	s_nop 0
	s_nop 0
	s_nop 0
	s_nop 0
	s_nop 0
	s_nop 0
	s_nop 0
	s_nop 0
	s_nop 0
	s_nop 0
	s_nop 0
	s_nop 0
	s_nop 0
	s_nop 0
	s_nop 0
	s_nop 0
	s_nop 0
	s_nop 0
	s_nop 0
	s_nop 0
	s_nop 0
	s_nop 0
	s_nop 0
	s_nop 0
	s_nop 0
	s_nop 0
	s_nop 0
	s_nop 0
	s_nop 0
	s_nop 0
	s_nop 0
	s_nop 0
	s_nop 0
	s_nop 0
	s_nop 0
	s_nop 0
	s_nop 0
	s_nop 0
	s_nop 0
	s_nop 0
	s_nop 0
	s_nop 0
	s_nop 0
	s_nop 0
	s_nop 0
	s_nop 0
	s_nop 0
	s_nop 0
	s_nop 0
	s_nop 0
	s_nop 0
	s_nop 0
	s_nop 0
	s_nop 0
	s_nop 0
	s_nop 0
	s_nop 0
	s_nop 0
	s_nop 0
	s_nop 0
	s_nop 0
	s_nop 0
	s_nop 0
	s_nop 0
	s_nop 0
	s_nop 0
	s_nop 0
	s_nop 0
	s_nop 0
	s_nop 0
	s_nop 0
	s_nop 0
	s_nop 0
	s_nop 0
	s_nop 0
	s_nop 0
	s_nop 0
	s_nop 0
	s_nop 0
	s_nop 0
	s_nop 0
	s_nop 0
	s_nop 0
	s_nop 0
	s_nop 0
	s_nop 0
	s_nop 0
	s_nop 0
	s_nop 0
	s_nop 0
	s_nop 0
	s_nop 0
	s_nop 0
	s_nop 0
	s_nop 0
	s_nop 0
	s_nop 0
	s_nop 0
	s_nop 0
	s_nop 0
	s_nop 0
	s_nop 0
	s_nop 0
	s_nop 0
	s_nop 0
	s_nop 0
	s_nop 0
	s_nop 0
	s_nop 0
	s_nop 0
	s_nop 0
	s_nop 0
	s_nop 0
	s_nop 0
	s_nop 0
	s_nop 0
	s_nop 0
	s_nop 0
	s_nop 0
	s_nop 0
	s_nop 0
	s_nop 0
	s_nop 0
	s_nop 0
	s_nop 0
	s_nop 0
	s_nop 0
	s_nop 0
	s_nop 0
	s_nop 0
	s_nop 0
	s_nop 0
	s_nop 0
	s_nop 0
	s_nop 0
	s_nop 0
	s_nop 0
	s_nop 0
	s_nop 0
	s_nop 0
	s_nop 0
	s_nop 0
	s_nop 0
	s_nop 0
	s_nop 0
	s_nop 0
	s_nop 0
	s_nop 0
	s_nop 0
	s_nop 0
	s_nop 0
	s_nop 0
	s_nop 0
	s_nop 0
	s_nop 0
	s_nop 0
	s_nop 0
	s_nop 0
	s_nop 0
; __device__ __forceinline__ void subln_store(f32x16 (&o)[4], const float* subg, bf16_t* dst  , int lane) {
;     ...
;         for (int g = 0; g < 4; ++g) sg[cb][g] = *(const f32x4*)(subg + 32 * cb + 8 * g + 4 * hi);
; __device__ __forceinline__ void attnA_unit(const P2Ctx& C, int b, int h, int qb) {
;     ...
;     if (comp == 0) {
; #pragma unroll
;         for (int cb = 0; cb < 4; ++cb)
; #pragma unroll
;             for (int r = 0; r < 16; ++r) o[cb][r] = o[cb][r] * inv - lam * X2[((qs * 4 + cb) * 16 + r) * 64 + lane];
.LaA_comp0_14:
	v_lshrrev_b32_e32 v242, 5, v219
	v_lshlrev_b32_e32 v242, 4, v242
	v_add_u32_e32 v242, 0x22a00, v242
	ds_read_b128 v[100:103], v242 offset:0
	ds_read_b128 v[104:107], v242 offset:32
	ds_read_b128 v[108:111], v242 offset:64
	ds_read_b128 v[112:115], v242 offset:96
	ds_read_b128 v[116:119], v242 offset:128
	ds_read_b128 v[120:123], v242 offset:160
	ds_read_b128 v[124:127], v242 offset:192
	ds_read_b128 v[128:131], v242 offset:224
	s_waitcnt lgkmcnt(4)
	ds_read_b128 v[132:135], v242 offset:256
	ds_read_b128 v[136:139], v242 offset:288
	ds_read_b128 v[140:143], v242 offset:320
	ds_read_b128 v[144:147], v242 offset:352
	ds_read_b128 v[148:151], v242 offset:384
	ds_read_b128 v[152:155], v242 offset:416
	ds_read_b128 v[156:159], v242 offset:448
	ds_read_b128 v[160:163], v242 offset:480
	s_waitcnt lgkmcnt(6)
	ds_read_b32 v243, v207
	s_nop 7
	s_nop 3
	v_mul_f32_e32 v4, v4, v241
	v_mul_f32_e32 v5, v5, v241
	v_mul_f32_e32 v6, v6, v241
	v_mul_f32_e32 v7, v7, v241
	v_mul_f32_e32 v8, v8, v241
	v_mul_f32_e32 v9, v9, v241
	v_mul_f32_e32 v10, v10, v241
	v_mul_f32_e32 v11, v11, v241
	v_mul_f32_e32 v12, v12, v241
	v_mul_f32_e32 v13, v13, v241
	v_mul_f32_e32 v14, v14, v241
	v_mul_f32_e32 v15, v15, v241
	v_mul_f32_e32 v16, v16, v241
	v_mul_f32_e32 v17, v17, v241
	v_mul_f32_e32 v18, v18, v241
	v_mul_f32_e32 v19, v19, v241
	v_mul_f32_e32 v20, v20, v241
	v_mul_f32_e32 v21, v21, v241
	v_mul_f32_e32 v22, v22, v241
	v_mul_f32_e32 v23, v23, v241
	v_mul_f32_e32 v24, v24, v241
	v_mul_f32_e32 v25, v25, v241
	v_mul_f32_e32 v26, v26, v241
	v_mul_f32_e32 v27, v27, v241
	v_mul_f32_e32 v28, v28, v241
	v_mul_f32_e32 v29, v29, v241
	v_mul_f32_e32 v30, v30, v241
	v_mul_f32_e32 v31, v31, v241
	v_mul_f32_e32 v32, v32, v241
	v_mul_f32_e32 v33, v33, v241
	v_mul_f32_e32 v34, v34, v241
	v_mul_f32_e32 v35, v35, v241
	v_mul_f32_e32 v36, v36, v241
	v_mul_f32_e32 v37, v37, v241
	v_mul_f32_e32 v38, v38, v241
	v_mul_f32_e32 v39, v39, v241
	v_mul_f32_e32 v40, v40, v241
	v_mul_f32_e32 v41, v41, v241
	v_mul_f32_e32 v42, v42, v241
	v_mul_f32_e32 v43, v43, v241
	v_mul_f32_e32 v44, v44, v241
	v_mul_f32_e32 v45, v45, v241
	v_mul_f32_e32 v46, v46, v241
	v_mul_f32_e32 v47, v47, v241
	v_mul_f32_e32 v48, v48, v241
	v_mul_f32_e32 v49, v49, v241
	v_mul_f32_e32 v50, v50, v241
	v_mul_f32_e32 v51, v51, v241
	v_mul_f32_e32 v52, v52, v241
	v_mul_f32_e32 v53, v53, v241
	v_mul_f32_e32 v54, v54, v241
	v_mul_f32_e32 v55, v55, v241
	v_mul_f32_e32 v56, v56, v241
	v_mul_f32_e32 v57, v57, v241
	v_mul_f32_e32 v58, v58, v241
	v_mul_f32_e32 v59, v59, v241
	v_mul_f32_e32 v60, v60, v241
	v_mul_f32_e32 v61, v61, v241
	v_mul_f32_e32 v62, v62, v241
	v_mul_f32_e32 v63, v63, v241
	v_mul_f32_e32 v64, v64, v241
	v_mul_f32_e32 v65, v65, v241
	v_mul_f32_e32 v66, v66, v241
	v_mul_f32_e32 v67, v67, v241
	s_waitcnt lgkmcnt(0)
	s_barrier
	ds_read2st64_b32 v[164:165], v2 offset0:0 offset1:1
	ds_read2st64_b32 v[166:167], v2 offset0:2 offset1:3
	ds_read2st64_b32 v[168:169], v2 offset0:4 offset1:5
	ds_read2st64_b32 v[170:171], v2 offset0:6 offset1:7
	ds_read2st64_b32 v[172:173], v2 offset0:8 offset1:9
	ds_read2st64_b32 v[174:175], v2 offset0:10 offset1:11
	ds_read2st64_b32 v[176:177], v2 offset0:12 offset1:13
	ds_read2st64_b32 v[178:179], v2 offset0:14 offset1:15
	ds_read2st64_b32 v[180:181], v2 offset0:16 offset1:17
	ds_read2st64_b32 v[182:183], v2 offset0:18 offset1:19
	ds_read2st64_b32 v[184:185], v2 offset0:20 offset1:21
	ds_read2st64_b32 v[186:187], v2 offset0:22 offset1:23
	ds_read2st64_b32 v[188:189], v2 offset0:24 offset1:25
	ds_read2st64_b32 v[190:191], v2 offset0:26 offset1:27
	ds_read2st64_b32 v[192:193], v2 offset0:28 offset1:29
	s_waitcnt lgkmcnt(8)
	ds_read2st64_b32 v[194:195], v2 offset0:30 offset1:31
	ds_read2st64_b32 v[68:69], v2 offset0:32 offset1:33
	ds_read2st64_b32 v[70:71], v2 offset0:34 offset1:35
	ds_read2st64_b32 v[72:73], v2 offset0:36 offset1:37
	ds_read2st64_b32 v[74:75], v2 offset0:38 offset1:39
	ds_read2st64_b32 v[76:77], v2 offset0:40 offset1:41
	ds_read2st64_b32 v[78:79], v2 offset0:42 offset1:43
	ds_read2st64_b32 v[80:81], v2 offset0:44 offset1:45
	ds_read2st64_b32 v[82:83], v2 offset0:46 offset1:47
	ds_read2st64_b32 v[84:85], v2 offset0:48 offset1:49
	ds_read2st64_b32 v[86:87], v2 offset0:50 offset1:51
	ds_read2st64_b32 v[88:89], v2 offset0:52 offset1:53
	ds_read2st64_b32 v[90:91], v2 offset0:54 offset1:55
	ds_read2st64_b32 v[92:93], v2 offset0:56 offset1:57
	ds_read2st64_b32 v[94:95], v2 offset0:58 offset1:59
	ds_read2st64_b32 v[96:97], v2 offset0:60 offset1:61
	ds_read2st64_b32 v[98:99], v2 offset0:62 offset1:63
	s_waitcnt lgkmcnt(0)
; __device__ __forceinline__ void subln_store(f32x16 (&o)[4], const float* subg, bf16_t* dst  , int lane) {
;     const int hi = lane >> 5;
;     float ss = 0.f;
; #pragma unroll
;     for (int cb = 0; cb < 4; ++cb)
; #pragma unroll
;         for (int r = 0; r < 16; ++r) ss += o[cb][r] * o[cb][r];
;     ss += __shfl_xor(ss, 32);
;     const float rstd = (1.0f - LAMBDA_INIT) / sqrtf(ss * (1.0f / 128.0f) + EPS);
; __device__ __forceinline__ void attnA_unit(const P2Ctx& C, int b, int h, int qb) {
;     ...
;             for (int r = 0; r < 16; ++r) o[cb][r] = o[cb][r] * inv - lam * X2[((qs * 4 + cb) * 16 + r) * 64 + lane];
	v_fma_f32 v4, -v243, v164, v4
	v_fma_f32 v5, -v243, v165, v5
	v_fma_f32 v6, -v243, v166, v6
	v_fma_f32 v7, -v243, v167, v7
	v_fma_f32 v8, -v243, v168, v8
	v_fma_f32 v9, -v243, v169, v9
	v_fma_f32 v10, -v243, v170, v10
	v_fma_f32 v11, -v243, v171, v11
	v_fma_f32 v12, -v243, v172, v12
	v_fma_f32 v13, -v243, v173, v13
	v_fma_f32 v14, -v243, v174, v14
	v_fma_f32 v15, -v243, v175, v15
	v_fma_f32 v16, -v243, v176, v16
	v_fma_f32 v17, -v243, v177, v17
	v_fma_f32 v18, -v243, v178, v18
	v_fma_f32 v19, -v243, v179, v19
	v_fma_f32 v20, -v243, v180, v20
	v_fma_f32 v21, -v243, v181, v21
	v_fma_f32 v22, -v243, v182, v22
	v_fma_f32 v23, -v243, v183, v23
	v_fma_f32 v24, -v243, v184, v24
	v_fma_f32 v25, -v243, v185, v25
	v_fma_f32 v26, -v243, v186, v26
	v_fma_f32 v27, -v243, v187, v27
	v_fma_f32 v28, -v243, v188, v28
	v_fma_f32 v29, -v243, v189, v29
	v_fma_f32 v30, -v243, v190, v30
	v_fma_f32 v31, -v243, v191, v31
	v_fma_f32 v32, -v243, v192, v32
	v_fma_f32 v33, -v243, v193, v33
	v_fma_f32 v34, -v243, v194, v34
	v_fma_f32 v35, -v243, v195, v35
	v_fma_f32 v36, -v243, v68, v36
	v_fma_f32 v37, -v243, v69, v37
	v_fma_f32 v38, -v243, v70, v38
	v_fma_f32 v39, -v243, v71, v39
	v_fma_f32 v40, -v243, v72, v40
	v_fma_f32 v41, -v243, v73, v41
	v_fma_f32 v42, -v243, v74, v42
	v_fma_f32 v43, -v243, v75, v43
	v_fma_f32 v44, -v243, v76, v44
	v_fma_f32 v45, -v243, v77, v45
	v_fma_f32 v46, -v243, v78, v46
	v_fma_f32 v47, -v243, v79, v47
	v_fma_f32 v48, -v243, v80, v48
	v_fma_f32 v49, -v243, v81, v49
	v_fma_f32 v50, -v243, v82, v50
	v_fma_f32 v51, -v243, v83, v51
	v_fma_f32 v52, -v243, v84, v52
	v_fma_f32 v53, -v243, v85, v53
	v_fma_f32 v54, -v243, v86, v54
	v_fma_f32 v55, -v243, v87, v55
	v_fma_f32 v56, -v243, v88, v56
	v_fma_f32 v57, -v243, v89, v57
	v_fma_f32 v58, -v243, v90, v58
	v_fma_f32 v59, -v243, v91, v59
	v_fma_f32 v60, -v243, v92, v60
	v_fma_f32 v61, -v243, v93, v61
	v_fma_f32 v62, -v243, v94, v62
	v_fma_f32 v63, -v243, v95, v63
	v_fma_f32 v64, -v243, v96, v64
	v_fma_f32 v65, -v243, v97, v65
	v_fma_f32 v66, -v243, v98, v66
	v_fma_f32 v67, -v243, v99, v67
	v_mul_f32_e32 v245, v4, v4
	v_fmac_f32_e32 v245, v5, v5
	v_fmac_f32_e32 v245, v6, v6
	v_fmac_f32_e32 v245, v7, v7
	v_fmac_f32_e32 v245, v8, v8
	v_fmac_f32_e32 v245, v9, v9
	v_fmac_f32_e32 v245, v10, v10
	v_fmac_f32_e32 v245, v11, v11
	v_fmac_f32_e32 v245, v12, v12
	v_fmac_f32_e32 v245, v13, v13
	v_fmac_f32_e32 v245, v14, v14
	v_fmac_f32_e32 v245, v15, v15
	v_fmac_f32_e32 v245, v16, v16
	v_fmac_f32_e32 v245, v17, v17
	v_fmac_f32_e32 v245, v18, v18
	v_fmac_f32_e32 v245, v19, v19
	v_fmac_f32_e32 v245, v20, v20
	v_fmac_f32_e32 v245, v21, v21
	v_fmac_f32_e32 v245, v22, v22
	v_fmac_f32_e32 v245, v23, v23
	v_fmac_f32_e32 v245, v24, v24
	v_fmac_f32_e32 v245, v25, v25
	v_fmac_f32_e32 v245, v26, v26
	v_fmac_f32_e32 v245, v27, v27
	v_fmac_f32_e32 v245, v28, v28
	v_fmac_f32_e32 v245, v29, v29
	v_fmac_f32_e32 v245, v30, v30
	v_fmac_f32_e32 v245, v31, v31
	v_fmac_f32_e32 v245, v32, v32
	v_fmac_f32_e32 v245, v33, v33
	v_fmac_f32_e32 v245, v34, v34
	v_fmac_f32_e32 v245, v35, v35
	v_fmac_f32_e32 v245, v36, v36
	v_fmac_f32_e32 v245, v37, v37
	v_fmac_f32_e32 v245, v38, v38
	v_fmac_f32_e32 v245, v39, v39
	v_fmac_f32_e32 v245, v40, v40
	v_fmac_f32_e32 v245, v41, v41
	v_fmac_f32_e32 v245, v42, v42
	v_fmac_f32_e32 v245, v43, v43
	v_fmac_f32_e32 v245, v44, v44
	v_fmac_f32_e32 v245, v45, v45
	v_fmac_f32_e32 v245, v46, v46
	v_fmac_f32_e32 v245, v47, v47
	v_fmac_f32_e32 v245, v48, v48
	v_fmac_f32_e32 v245, v49, v49
	v_fmac_f32_e32 v245, v50, v50
	v_fmac_f32_e32 v245, v51, v51
	v_fmac_f32_e32 v245, v52, v52
	v_fmac_f32_e32 v245, v53, v53
	v_fmac_f32_e32 v245, v54, v54
	v_fmac_f32_e32 v245, v55, v55
	v_fmac_f32_e32 v245, v56, v56
	v_fmac_f32_e32 v245, v57, v57
	v_fmac_f32_e32 v245, v58, v58
	v_fmac_f32_e32 v245, v59, v59
	v_fmac_f32_e32 v245, v60, v60
	v_fmac_f32_e32 v245, v61, v61
	v_fmac_f32_e32 v245, v62, v62
	v_fmac_f32_e32 v245, v63, v63
	v_fmac_f32_e32 v245, v64, v64
	v_fmac_f32_e32 v245, v65, v65
	v_fmac_f32_e32 v245, v66, v66
	v_fmac_f32_e32 v245, v67, v67
	v_mov_b32_e32 v246, v245
	s_nop 1
	v_permlane32_swap_b32 v246, v245
	v_add_f32_e32 v245, v246, v245
	v_mov_b32_e32 v246, 0x3c000000
	v_fmaak_f32 v245, v245, v246, 0x358637bd
	v_rsq_f32_e32 v245, v245
	s_nop 0
	v_mul_f32_e32 v245, 0x3f4ccccd, v245
	s_lshl_b32 s6, s11, 11
	s_add_i32 s6, s6, s15
	s_lshl_b32 s6, s6, 11
	s_lshl_b32 s7, s81, 1
	s_add_i32 s6, s6, s7
	s_add_u32 s20, s70, s6
	s_addc_u32 s21, s71, 0
	v_and_b32_e32 v242, 31, v219
	v_lshlrev_b32_e32 v242, 11, v242
	v_lshrrev_b32_e32 v243, 5, v219
	v_lshl_add_u32 v242, v243, 3, v242
	s_waitcnt vmcnt(0)
; __device__ __forceinline__ unsigned pk_bf16(float lo, float hi) { f32x2 v = {lo, hi}; bf16x2_t b = __builtin_convertvector(v, bf16x2_t); return __builtin_bit_cast(unsigned, b); }
; __device__ __forceinline__ void subln_store(f32x16 (&o)[4], const float* subg, bf16_t* dst  , int lane) {
;     ...
;     f32x4 sg[4][4];
; #pragma unroll
;     for (int cb = 0; cb < 4; ++cb)
; #pragma unroll
;         for (int g = 0; g < 4; ++g) sg[cb][g] = *(const f32x4*)(subg + 32 * cb + 8 * g + 4 * hi);
;     asm volatile("" ::: "memory");
; #pragma unroll
;     for (int cb = 0; cb < 4; ++cb)
; #pragma unroll
;         for (int g = 0; g < 4; ++g) { const int dv0 = 32 * cb + 8 * g + 4 * hi; const f32x4 s4 = sg[cb][g];
;             u32x2 w; w.x = pk_bf16(o[cb][4 * g + 0] * rstd * s4[0], o[cb][4 * g + 1] * rstd * s4[1]); w.y = pk_bf16(o[cb][4 * g + 2] * rstd * s4[2], o[cb][4 * g + 3] * rstd * s4[3]);
;             *(u32x2*)(dst + dv0) = w; }
	v_mul_f32_e32 v4, v4, v245
	v_mul_f32_e32 v5, v5, v245
	v_mul_f32_e32 v6, v6, v245
	v_mul_f32_e32 v7, v7, v245
	v_mul_f32_e32 v4, v4, v100
	v_mul_f32_e32 v5, v5, v101
	v_mul_f32_e32 v6, v6, v102
	v_mul_f32_e32 v7, v7, v103
	v_cvt_pk_bf16_f32 v68, v4, v5
	v_cvt_pk_bf16_f32 v69, v6, v7
	global_store_dwordx2 v242, v[68:69], s[20:21] offset:0
	v_mul_f32_e32 v8, v8, v245
	v_mul_f32_e32 v9, v9, v245
	v_mul_f32_e32 v10, v10, v245
	v_mul_f32_e32 v11, v11, v245
	v_mul_f32_e32 v8, v8, v104
	v_mul_f32_e32 v9, v9, v105
	v_mul_f32_e32 v10, v10, v106
	v_mul_f32_e32 v11, v11, v107
	v_cvt_pk_bf16_f32 v70, v8, v9
	v_cvt_pk_bf16_f32 v71, v10, v11
	global_store_dwordx2 v242, v[70:71], s[20:21] offset:16
	v_mul_f32_e32 v12, v12, v245
	v_mul_f32_e32 v13, v13, v245
	v_mul_f32_e32 v14, v14, v245
	v_mul_f32_e32 v15, v15, v245
	v_mul_f32_e32 v12, v12, v108
	v_mul_f32_e32 v13, v13, v109
	v_mul_f32_e32 v14, v14, v110
	v_mul_f32_e32 v15, v15, v111
	v_cvt_pk_bf16_f32 v68, v12, v13
	v_cvt_pk_bf16_f32 v69, v14, v15
	global_store_dwordx2 v242, v[68:69], s[20:21] offset:32
	v_mul_f32_e32 v16, v16, v245
	v_mul_f32_e32 v17, v17, v245
	v_mul_f32_e32 v18, v18, v245
	v_mul_f32_e32 v19, v19, v245
	v_mul_f32_e32 v16, v16, v112
	v_mul_f32_e32 v17, v17, v113
	v_mul_f32_e32 v18, v18, v114
	v_mul_f32_e32 v19, v19, v115
	v_cvt_pk_bf16_f32 v70, v16, v17
	v_cvt_pk_bf16_f32 v71, v18, v19
	global_store_dwordx2 v242, v[70:71], s[20:21] offset:48
	v_mul_f32_e32 v20, v20, v245
	v_mul_f32_e32 v21, v21, v245
	v_mul_f32_e32 v22, v22, v245
	v_mul_f32_e32 v23, v23, v245
	v_mul_f32_e32 v20, v20, v116
	v_mul_f32_e32 v21, v21, v117
	v_mul_f32_e32 v22, v22, v118
	v_mul_f32_e32 v23, v23, v119
	v_cvt_pk_bf16_f32 v68, v20, v21
	v_cvt_pk_bf16_f32 v69, v22, v23
	global_store_dwordx2 v242, v[68:69], s[20:21] offset:64
	v_mul_f32_e32 v24, v24, v245
	v_mul_f32_e32 v25, v25, v245
	v_mul_f32_e32 v26, v26, v245
	v_mul_f32_e32 v27, v27, v245
	v_mul_f32_e32 v24, v24, v120
	v_mul_f32_e32 v25, v25, v121
	v_mul_f32_e32 v26, v26, v122
	v_mul_f32_e32 v27, v27, v123
	v_cvt_pk_bf16_f32 v70, v24, v25
	v_cvt_pk_bf16_f32 v71, v26, v27
	global_store_dwordx2 v242, v[70:71], s[20:21] offset:80
	v_mul_f32_e32 v28, v28, v245
	v_mul_f32_e32 v29, v29, v245
	v_mul_f32_e32 v30, v30, v245
	v_mul_f32_e32 v31, v31, v245
	v_mul_f32_e32 v28, v28, v124
	v_mul_f32_e32 v29, v29, v125
	v_mul_f32_e32 v30, v30, v126
	v_mul_f32_e32 v31, v31, v127
	v_cvt_pk_bf16_f32 v68, v28, v29
	v_cvt_pk_bf16_f32 v69, v30, v31
	global_store_dwordx2 v242, v[68:69], s[20:21] offset:96
	v_mul_f32_e32 v32, v32, v245
	v_mul_f32_e32 v33, v33, v245
	v_mul_f32_e32 v34, v34, v245
	v_mul_f32_e32 v35, v35, v245
	v_mul_f32_e32 v32, v32, v128
	v_mul_f32_e32 v33, v33, v129
	v_mul_f32_e32 v34, v34, v130
	v_mul_f32_e32 v35, v35, v131
	v_cvt_pk_bf16_f32 v70, v32, v33
	v_cvt_pk_bf16_f32 v71, v34, v35
	global_store_dwordx2 v242, v[70:71], s[20:21] offset:112
	v_mul_f32_e32 v36, v36, v245
	v_mul_f32_e32 v37, v37, v245
	v_mul_f32_e32 v38, v38, v245
	v_mul_f32_e32 v39, v39, v245
	v_mul_f32_e32 v36, v36, v132
	v_mul_f32_e32 v37, v37, v133
	v_mul_f32_e32 v38, v38, v134
	v_mul_f32_e32 v39, v39, v135
	v_cvt_pk_bf16_f32 v68, v36, v37
	v_cvt_pk_bf16_f32 v69, v38, v39
	global_store_dwordx2 v242, v[68:69], s[20:21] offset:128
	v_mul_f32_e32 v40, v40, v245
	v_mul_f32_e32 v41, v41, v245
	v_mul_f32_e32 v42, v42, v245
	v_mul_f32_e32 v43, v43, v245
	v_mul_f32_e32 v40, v40, v136
	v_mul_f32_e32 v41, v41, v137
	v_mul_f32_e32 v42, v42, v138
	v_mul_f32_e32 v43, v43, v139
	v_cvt_pk_bf16_f32 v70, v40, v41
	v_cvt_pk_bf16_f32 v71, v42, v43
	global_store_dwordx2 v242, v[70:71], s[20:21] offset:144
	v_mul_f32_e32 v44, v44, v245
	v_mul_f32_e32 v45, v45, v245
	v_mul_f32_e32 v46, v46, v245
	v_mul_f32_e32 v47, v47, v245
	v_mul_f32_e32 v44, v44, v140
	v_mul_f32_e32 v45, v45, v141
	v_mul_f32_e32 v46, v46, v142
	v_mul_f32_e32 v47, v47, v143
	v_cvt_pk_bf16_f32 v68, v44, v45
	v_cvt_pk_bf16_f32 v69, v46, v47
	global_store_dwordx2 v242, v[68:69], s[20:21] offset:160
	v_mul_f32_e32 v48, v48, v245
	v_mul_f32_e32 v49, v49, v245
	v_mul_f32_e32 v50, v50, v245
	v_mul_f32_e32 v51, v51, v245
	v_mul_f32_e32 v48, v48, v144
	v_mul_f32_e32 v49, v49, v145
	v_mul_f32_e32 v50, v50, v146
	v_mul_f32_e32 v51, v51, v147
	v_cvt_pk_bf16_f32 v70, v48, v49
	v_cvt_pk_bf16_f32 v71, v50, v51
	global_store_dwordx2 v242, v[70:71], s[20:21] offset:176
	v_mul_f32_e32 v52, v52, v245
	v_mul_f32_e32 v53, v53, v245
	v_mul_f32_e32 v54, v54, v245
	v_mul_f32_e32 v55, v55, v245
	v_mul_f32_e32 v52, v52, v148
	v_mul_f32_e32 v53, v53, v149
	v_mul_f32_e32 v54, v54, v150
	v_mul_f32_e32 v55, v55, v151
	v_cvt_pk_bf16_f32 v68, v52, v53
	v_cvt_pk_bf16_f32 v69, v54, v55
	global_store_dwordx2 v242, v[68:69], s[20:21] offset:192
	v_mul_f32_e32 v56, v56, v245
	v_mul_f32_e32 v57, v57, v245
	v_mul_f32_e32 v58, v58, v245
	v_mul_f32_e32 v59, v59, v245
	v_mul_f32_e32 v56, v56, v152
	v_mul_f32_e32 v57, v57, v153
	v_mul_f32_e32 v58, v58, v154
	v_mul_f32_e32 v59, v59, v155
	v_cvt_pk_bf16_f32 v70, v56, v57
	v_cvt_pk_bf16_f32 v71, v58, v59
	global_store_dwordx2 v242, v[70:71], s[20:21] offset:208
	v_mul_f32_e32 v60, v60, v245
	v_mul_f32_e32 v61, v61, v245
	v_mul_f32_e32 v62, v62, v245
	v_mul_f32_e32 v63, v63, v245
	v_mul_f32_e32 v60, v60, v156
	v_mul_f32_e32 v61, v61, v157
	v_mul_f32_e32 v62, v62, v158
	v_mul_f32_e32 v63, v63, v159
	v_cvt_pk_bf16_f32 v68, v60, v61
	v_cvt_pk_bf16_f32 v69, v62, v63
	global_store_dwordx2 v242, v[68:69], s[20:21] offset:224
	v_mul_f32_e32 v64, v64, v245
	v_mul_f32_e32 v65, v65, v245
	v_mul_f32_e32 v66, v66, v245
	v_mul_f32_e32 v67, v67, v245
	v_mul_f32_e32 v64, v64, v160
	v_mul_f32_e32 v65, v65, v161
	v_mul_f32_e32 v66, v66, v162
	v_mul_f32_e32 v67, v67, v163
	v_cvt_pk_bf16_f32 v70, v64, v65
	v_cvt_pk_bf16_f32 v71, v66, v67
	global_store_dwordx2 v242, v[70:71], s[20:21] offset:240
